# dropped the vmcnt(0) at the GEMM unit seam (it only waited for write-through store acks; K-loop counted waits and phase-end drain cover them)
# speedup vs baseline: 1.0184x; 1.0184x over previous
.LBB0_168:
	s_add_u32 s80, s80, 0x80
	s_addc_u32 s81, s81, 0
	s_add_u32 vcc_lo, s34, 0x100
	v_add_u32_e32 v206, 0x10000, v234
	v_add_u32_e32 v207, 0x14000, v234
	v_add_u32_e32 v208, 0x18000, v234
	v_add_u32_e32 v209, 0x1c000, v234
	v_mov_b32_e32 v2, 0
	s_addc_u32 vcc_hi, s35, 0
	s_mov_b32 s34, 0
	v_mov_b32_e32 v3, v2
	v_mov_b32_e32 v4, v2
	v_mov_b32_e32 v5, v2
	v_mov_b32_e32 v6, v2
	v_mov_b32_e32 v7, v2
	v_mov_b32_e32 v8, v2
	v_mov_b32_e32 v9, v2
	v_mov_b32_e32 v18, v2
	v_mov_b32_e32 v19, v2
	v_mov_b32_e32 v20, v2
	v_mov_b32_e32 v21, v2
	v_mov_b32_e32 v22, v2
	v_mov_b32_e32 v23, v2
	v_mov_b32_e32 v24, v2
	v_mov_b32_e32 v25, v2
	v_mov_b32_e32 v34, v2
	v_mov_b32_e32 v35, v2
	v_mov_b32_e32 v36, v2
	v_mov_b32_e32 v37, v2
	v_mov_b32_e32 v38, v2
	v_mov_b32_e32 v39, v2
	v_mov_b32_e32 v40, v2
	v_mov_b32_e32 v41, v2
	v_mov_b32_e32 v50, v2
	v_mov_b32_e32 v51, v2
	v_mov_b32_e32 v52, v2
	v_mov_b32_e32 v53, v2
	v_mov_b32_e32 v54, v2
	v_mov_b32_e32 v55, v2
	v_mov_b32_e32 v56, v2
	v_mov_b32_e32 v57, v2
	v_mov_b32_e32 v10, v2
	v_mov_b32_e32 v11, v2
	v_mov_b32_e32 v12, v2
	v_mov_b32_e32 v13, v2
	v_mov_b32_e32 v14, v2
	v_mov_b32_e32 v15, v2
	v_mov_b32_e32 v16, v2
	v_mov_b32_e32 v17, v2
	v_mov_b32_e32 v26, v2
	v_mov_b32_e32 v27, v2
	v_mov_b32_e32 v28, v2
	v_mov_b32_e32 v29, v2
	v_mov_b32_e32 v30, v2
	v_mov_b32_e32 v31, v2
	v_mov_b32_e32 v32, v2
	v_mov_b32_e32 v33, v2
	v_mov_b32_e32 v42, v2
	v_mov_b32_e32 v43, v2
	v_mov_b32_e32 v44, v2
	v_mov_b32_e32 v45, v2
	v_mov_b32_e32 v46, v2
	v_mov_b32_e32 v47, v2
	v_mov_b32_e32 v48, v2
	v_mov_b32_e32 v49, v2
	v_mov_b32_e32 v58, v2
	v_mov_b32_e32 v59, v2
	v_mov_b32_e32 v60, v2
	v_mov_b32_e32 v61, v2
	v_mov_b32_e32 v62, v2
	v_mov_b32_e32 v63, v2
	v_mov_b32_e32 v64, v2
	v_mov_b32_e32 v65, v2
	v_mov_b32_e32 v66, v2
	v_mov_b32_e32 v67, v2
	v_mov_b32_e32 v68, v2
	v_mov_b32_e32 v69, v2
	v_mov_b32_e32 v70, v2
	v_mov_b32_e32 v71, v2
	v_mov_b32_e32 v72, v2
	v_mov_b32_e32 v73, v2
	v_mov_b32_e32 v82, v2
	v_mov_b32_e32 v83, v2
	v_mov_b32_e32 v84, v2
	v_mov_b32_e32 v85, v2
	v_mov_b32_e32 v86, v2
	v_mov_b32_e32 v87, v2
	v_mov_b32_e32 v88, v2
	v_mov_b32_e32 v89, v2
	v_mov_b32_e32 v98, v2
	v_mov_b32_e32 v99, v2
	v_mov_b32_e32 v100, v2
	v_mov_b32_e32 v101, v2
	v_mov_b32_e32 v106, v2
	v_mov_b32_e32 v107, v2
	v_mov_b32_e32 v108, v2
	v_mov_b32_e32 v109, v2
	v_mov_b32_e32 v110, v2
	v_mov_b32_e32 v111, v2
	v_mov_b32_e32 v112, v2
	v_mov_b32_e32 v113, v2
	v_mov_b32_e32 v114, v2
	v_mov_b32_e32 v115, v2
	v_mov_b32_e32 v116, v2
	v_mov_b32_e32 v117, v2
	v_mov_b32_e32 v74, v2
	v_mov_b32_e32 v75, v2
	v_mov_b32_e32 v76, v2
	v_mov_b32_e32 v77, v2
	v_mov_b32_e32 v78, v2
	v_mov_b32_e32 v79, v2
	v_mov_b32_e32 v80, v2
	v_mov_b32_e32 v81, v2
	v_mov_b32_e32 v90, v2
	v_mov_b32_e32 v91, v2
	v_mov_b32_e32 v92, v2
	v_mov_b32_e32 v93, v2
	v_mov_b32_e32 v94, v2
	v_mov_b32_e32 v95, v2
	v_mov_b32_e32 v96, v2
	v_mov_b32_e32 v97, v2
	v_mov_b32_e32 v102, v2
	v_mov_b32_e32 v103, v2
	v_mov_b32_e32 v104, v2
	v_mov_b32_e32 v105, v2
	v_mov_b32_e32 v118, v2
	v_mov_b32_e32 v119, v2
	v_mov_b32_e32 v120, v2
	v_mov_b32_e32 v121, v2
	v_mov_b32_e32 v122, v2
	v_mov_b32_e32 v123, v2
	v_mov_b32_e32 v124, v2
	v_mov_b32_e32 v125, v2
	v_mov_b32_e32 v126, v2
	v_mov_b32_e32 v127, v2
	v_mov_b32_e32 v128, v2
	v_mov_b32_e32 v129, v2
